# HG chains staggered by two barriers (VALU stage of one chain beside MFMA stage of the other); static prio for waves 4-7 in SSD loop
# baseline (speedup 1.0000x reference)
; #define LAS __attribute__((address_space(3)))
; DI void ssd_unit(LAS unsigned char* lds, const MixL& P, int b, int g) {
;     int tid_l = threadIdx.x; asm volatile("" : "+v"(tid_l));
;     const int tid = tid_l, lane = tid & 63, wave = __builtin_amdgcn_readfirstlane(tid >> 6), l15 = lane & 15, q = lane >> 4;
;     const int r = wave >> 1, hh = wave & 1;
;     LAS unsigned char* XT = lds; LAS unsigned char* BMp = lds + 36864; LAS unsigned char* BTp = lds + 46080; LAS unsigned char* CMp = lds + 55296;
;     LAS float* ACUM = (LAS float*)(lds + 64512); LAS float* DTV = ACUM + 256; LAS float* EA = ACUM + 512; LAS float* WV = ACUM + 768; LAS float* SSQP = ACUM + 1024;
;     const float Dr = P.dskip[4 * g + r];
;     const size_t rowbase = (size_t)b * SEQ;
;     const int ycol = 256 * g + 64 * r + 32 * hh + 4 * q;
;     const LAS unsigned char* XTr = XT + r * 64 * LS;
;     const LAS float* ac = ACUM + r * 64; const LAS float* dtv = DTV + r * 64; const LAS float* ea = EA + r * 64; const LAS float* wv = WV + r * 64;
;     f32x4 ST[4][2];
; #pragma unroll
;     for (int i = 0; i < 4; ++i)
; #pragma unroll
;         for (int j = 0; j < 2; ++j) ST[i][j] = (f32x4){0.f, 0.f, 0.f, 0.f};
;     f32x4 nwv[2];
; #pragma unroll
;     for (int pt = 0; pt < 2; ++pt) nwv[pt] = *(const f32x4*)(P.ssd_nw + ycol + 16 * pt);
;     ssd_dma(lds, P, rowbase, b, g, 0, tid, wave);
.LBB0_501:
	s_lshl_b32 s6, s33, 2
	s_add_i32 s8, s6, 0
	s_mul_i32 s7, s11, 0x2300
	s_add_i32 s38, s8, 0x10400
	s_add_i32 s6, s8, 0x10000
	v_and_b32_e32 v24, 15, v22
	s_add_i32 s9, s8, s7
	s_add_i32 s46, s8, 0x10800
	v_cndmask_b32_e64 v5, 0, 1, s[66:67]
	v_lshlrev_b32_e32 v25, 6, v5
	v_lshlrev_b32_e32 v27, 8, v5
	v_lshlrev_b32_e32 v5, 2, v24
	v_readlane_b32 s4, v254, 36
	s_cmp_gt_i32 s13, 1
	s_cselect_b64 s[52:53], -1, 0
	v_add_u32_e32 v210, s4, v5
	s_cmp_lt_i32 s13, 2
	s_movk_i32 s4, 0x200
	s_cselect_b32 s48, s4, 0x280
	v_or_b32_e32 v33, s54, v24
	v_mov_b32_e32 v40, s9
	s_movk_i32 s4, 0x90
	v_mad_u32_u24 v33, v33, s4, v40
	v_mad_u32_u24 v219, v24, s4, 0
	v_readlane_b32 s4, v253, 19
	v_lshlrev_b64 v[18:19], 2, v[18:19]
	v_readlane_b32 s5, v253, 20
	v_lshlrev_b32_e32 v34, 2, v9
	v_add_u32_e32 v216, s38, v5
	v_lshl_add_u64 v[18:19], s[4:5], 0, v[18:19]
	v_lshl_add_u64 v[16:17], v[16:17], 2, v[18:19]
	s_movk_i32 s4, 0x600
	v_add_u32_e32 v217, s8, v5
	v_or_b32_e32 v5, 1, v9
	v_add_u32_e32 v218, s46, v34
	v_lshl_add_u64 v[170:171], v[6:7], 2, v[16:17]
	v_mad_u64_u32 v[6:7], s[46:47], v14, s4, 0
	v_cmp_eq_u32_e64 s[14:15], v5, v24
	v_or_b32_e32 v5, 2, v9
	v_mov_b32_e32 v14, v7
	v_cmp_gt_u32_e64 s[16:17], v5, v24
	v_cmp_eq_u32_e64 s[18:19], v5, v24
	v_or_b32_e32 v5, 3, v9
	v_mad_u64_u32 v[14:15], s[46:47], v15, s4, v[14:15]
	v_cmp_gt_u32_e64 s[20:21], v5, v24
	v_cmp_eq_u32_e64 s[22:23], v5, v24
	v_mov_b32_e32 v7, v14
	v_or_b32_e32 v5, s48, v25
	v_mad_i64_i32 v[6:7], s[46:47], s24, v206, v[6:7]
	v_add_u32_e32 v14, v5, v23
	v_mov_b32_e32 v15, v8
	v_lshl_add_u64 v[6:7], v[14:15], 1, v[6:7]
	v_lshl_add_u64 v[172:173], s[28:29], 0, v[6:7]
	v_mad_i64_i32 v[4:5], s[46:47], v4, s4, 0
	v_or_b32_e32 v6, v27, v20
	v_mad_i64_i32 v[4:5], s[46:47], s24, v206, v[4:5]
	v_lshlrev_b32_e32 v6, 1, v6
	v_mov_b32_e32 v7, v8
	v_lshl_add_u64 v[4:5], v[4:5], 0, v[6:7]
	s_cselect_b32 s7, 32, 40
	s_lshl_b32 s11, s11, 2
	s_and_b32 s10, s10, 0x3fffffc0
	s_add_i32 s68, s68, 1
	v_lshl_add_u64 v[174:175], s[28:29], 0, v[4:5]
	v_add_u32_e32 v4, s33, v27
	s_lshl_b64 s[46:47], s[24:25], 22
	v_bfe_u32 v32, v22, 3, 1
	v_add_u32_e32 v4, s54, v4
	s_add_u32 s46, s30, s46
	v_lshl_or_b32 v32, s12, 1, v32
	v_add_u32_e32 v4, v4, v9
	s_addc_u32 s47, s31, s47
	s_mul_hi_i32 s25, s24, 0xe00000
	s_mul_i32 s24, s24, 0xe00000
	v_and_or_b32 v28, v22, 7, s7
	v_bfe_u32 v29, v22, 3, 4
	v_ashrrev_i32_e32 v30, 5, v22
	v_lshlrev_b32_e32 v211, 4, v22
	v_lshlrev_b32_e32 v212, 3, v21
	v_add_u32_e32 v214, s6, v34
	v_cmp_eq_u32_e64 s[6:7], 0, v21
	v_and_b32_e32 v22, 1, v22
	v_and_b32_e32 v26, 14, v26
	v_mov_b32_e32 v36, 0xffffff00
	v_bitop3_b32 v39, v32, v21, s11 bitop3:0x36
	v_or_b32_e32 v40, 4, v21
	v_or_b32_e32 v41, 8, v21
	v_or_b32_e32 v21, 12, v21
	v_ashrrev_i32_e32 v5, 31, v4
	s_add_u32 s24, s30, s24
	v_bitop3_b32 v22, v26, v30, v22 bitop3:0x36
	v_lshl_add_u32 v36, v28, 3, v36
	v_bitop3_b32 v40, v32, v40, s11 bitop3:0x36
	v_bitop3_b32 v41, v32, v41, s11 bitop3:0x36
	v_bitop3_b32 v21, v32, v21, s11 bitop3:0x36
	v_lshlrev_b64 v[176:177], 1, v[4:5]
	v_lshlrev_b32_e32 v4, 11, v24
	v_mov_b32_e32 v5, v8
	s_addc_u32 s25, s31, s25
	v_add_u32_e32 v31, 0, v212
	v_add_u32_e32 v213, s8, v34
	v_lshl_add_u32 v22, v22, 3, 0
	v_mul_u32_u24_e32 v26, 0x90, v20
	v_lshl_add_u32 v30, v28, 4, 0
	v_mul_u32_u24_e32 v35, 0x240, v29
	v_lshl_add_u32 v37, v36, 1, 0
	v_lshl_add_u32 v29, v29, 3, 0
	v_mul_u32_u24_e32 v36, 0x90, v36
	v_mul_u32_u24_e32 v28, 0x480, v28
	v_mul_u32_u24_e32 v38, 0x90, v24
	v_lshlrev_b32_e32 v39, 3, v39
	v_lshlrev_b32_e32 v40, 3, v40
	v_lshlrev_b32_e32 v41, 3, v41
	v_lshlrev_b32_e32 v21, 3, v21
	v_add_u32_e32 v32, 0x900, v219
	v_add_u32_e32 v34, 0x1200, v219
	v_lshl_add_u64 v[178:179], s[46:47], 0, v[4:5]
	v_mov_b64_e32 v[4:5], s[24:25]
	v_mov_b32_e32 v14, 0
	v_lshl_add_u32 v215, s10, 2, v210
	v_cmp_gt_u32_e64 s[8:9], v9, v24
	v_cmp_eq_u32_e64 s[10:11], v9, v24
	v_cmp_lt_u32_e64 s[12:13], v9, v24
	v_mad_u64_u32 v[180:181], s[24:25], v24, s27, v[4:5]
	s_mov_b64 s[70:71], 0
	v_add_u32_e32 v220, v22, v26
	v_add_u32_e32 v221, v30, v35
	v_add_u32_e32 v222, v37, v35
	v_add_u32_e32 v223, v29, v36
	v_add_u32_e32 v224, v29, v28
	v_add_u32_e32 v225, v31, v38
	v_add_u32_e32 v226, v33, v39
	v_add_u32_e32 v227, v33, v40
	v_add_u32_e32 v228, v33, v41
	v_add_u32_e32 v229, v33, v21
	v_add_u32_e32 v230, v32, v212
	v_add_u32_e32 v231, v34, v212
	v_mov_b32_e32 v15, v14
	v_mov_b32_e32 v16, v14
	v_mov_b32_e32 v17, v14
	v_mov_b32_e32 v18, v14
	v_mov_b32_e32 v19, v14
	v_mov_b32_e32 v20, v14
	v_mov_b32_e32 v21, v14
	v_mov_b32_e32 v22, v14
	v_mov_b32_e32 v23, v14
	v_mov_b32_e32 v24, v14
	v_mov_b32_e32 v25, v14
	v_mov_b32_e32 v26, v14
	v_mov_b32_e32 v27, v14
	v_mov_b32_e32 v28, v14
	v_mov_b32_e32 v29, v14
	v_mov_b32_e32 v30, v14
	v_mov_b32_e32 v31, v14
	v_mov_b32_e32 v32, v14
	v_mov_b32_e32 v33, v14
	v_mov_b32_e32 v38, v14
	v_mov_b32_e32 v39, v14
	v_mov_b32_e32 v40, v14
	v_mov_b32_e32 v41, v14
	v_mov_b32_e32 v34, v14
	v_mov_b32_e32 v35, v14
	v_mov_b32_e32 v36, v14
	v_mov_b32_e32 v37, v14
	v_mov_b32_e32 v42, v14
	v_mov_b32_e32 v43, v14
	v_mov_b32_e32 v44, v14
	v_mov_b32_e32 v45, v14
	s_cmp_lg_u64 s[40:41], 0
	s_cbranch_scc1 .LBB0_503
	s_setprio 1
	s_branch .LBB0_503

; #define LAS __attribute__((address_space(3)))
; DI void hg_unit(LAS unsigned char* lds, const MixL& P, int pi) {
;     int tid_l = threadIdx.x; asm volatile("" : "+v"(tid_l));
;     const int tid = tid_l, lane = tid & 63, wave = __builtin_amdgcn_readfirstlane(tid >> 6), l15 = lane & 15, q = lane >> 4;
;     const int chain = wave >> 2, wv = wave & 3, ci = 2 * pi + chain, b = ci >> 3, h = ci & 7;
;     LAS unsigned char* base = lds + chain * 40960;
;     LAS unsigned char* QE = base; LAS unsigned char* KE = base + 9216; LAS unsigned char* KET = base + 18432; LAS unsigned char* VT = base + 27648;
;     LAS float* EBREF = (LAS float*)(base + 36864); LAS float* EBLR = EBREF + 64; LAS float* EBLAST = EBREF + 128; LAS float* CUMQ = EBREF + 192; LAS float* SSQP = EBREF + 448;
;     const int d = lane, tq = wv;
;     const float lb = P.lb[64 * h + d], oml = 1.0f - lb;
;     const size_t rowbase = (size_t)b * SEQ;
;     const int ycol = 64 * h + 16 * wv + 4 * q;
;     f32x4 SD[4];
; #pragma unroll
;     for (int i = 0; i < 4; ++i) SD[i] = (f32x4){0.f, 0.f, 0.f, 0.f};
;     const f32x4 nw = *(const f32x4*)(P.hg_nw + 16 * wv + 4 * q);
;     hg_dma(lds, P, rowbase, h, 0, tid, wave);
.LBB0_521:
	s_setprio 0
	s_cmp_lt_i32 s73, 64
	s_cbranch_scc1 .LBB0_495
	v_mov_b32_e32 v9, v200
	s_lshl_b32 s0, s73, 1
	v_readfirstlane_b32 s10, v9
	s_ashr_i32 s33, s10, 8
	s_add_i32 s0, s0, s33
	s_addk_i32 s0, 0xff80
	s_lshl_b32 s1, s0, 6
	v_and_b32_e32 v18, 63, v9
	s_and_b32 s11, s1, 0x1c0
	s_ashr_i32 s20, s0, 3
	v_or_b32_e32 v0, s11, v18
	v_readlane_b32 s4, v254, 61
	s_ashr_i32 s12, s10, 6
	s_mul_i32 s1, s33, 0xa000
	s_ashr_i32 s21, s20, 31
	v_lshlrev_b32_e32 v0, 2, v0
	v_readlane_b32 s5, v254, 62
	v_lshrrev_b32_e32 v3, 2, v9
	s_and_b32 s13, s12, 3
	s_add_i32 s14, s1, 0
	s_lshl_b64 s[0:1], s[20:21], 11
	v_lshlrev_b32_e32 v6, 1, v9
	global_load_dword v122, v0, s[4:5]
	v_mov_b64_e32 v[0:1], s[64:65]
	s_lshl_b32 s46, s13, 4
	s_lshl_b32 s15, s13, 6
	v_readlane_b32 s4, v254, 63
	v_and_or_b32 v3, v3, 62, s0
	v_and_b32_e32 v22, 14, v6
	s_add_u32 s6, s4, s15
	v_readlane_b32 s0, v255, 0
	v_mad_u64_u32 v[6:7], s[8:9], v3, s27, v[0:1]
	v_lshlrev_b32_e32 v4, 4, v9
	s_addc_u32 s7, s0, 0
	s_lshl_b32 s38, s11, 1
	v_mad_i32_i24 v7, s1, v207, v7
	v_mov_b32_e32 v5, v8
	v_bfe_u32 v10, v9, 3, 3
	v_and_b32_e32 v4, 0x70, v4
	s_and_b32 s0, s10, 0xfffff00
	v_lshl_add_u64 v[6:7], v[6:7], 0, s[38:39]
	s_lshl_b32 s8, s12, 10
	s_add_i32 s12, 0, 0x14000
	v_or_b32_e32 v10, s0, v10
	v_lshl_add_u64 v[4:5], v[6:7], 0, v[4:5]
	s_mov_b64 s[0:1], 0xa00
	s_add_i32 s16, 0, 0x16000
	s_add_i32 m0, s12, s8
	s_add_i32 s24, s8, 0
	v_lshl_add_u64 v[6:7], v[4:5], 0, s[0:1]
	s_mov_b64 s[0:1], 0x2600
	s_add_i32 s25, s24, 0x18000
	v_or_b32_e32 v24, s15, v10
	v_lshl_add_u64 v[10:11], v[4:5], 0, s[0:1]
	s_mov_b64 s[0:1], 0xe00
	global_load_lds_dwordx4 v[6:7], off
	s_add_i32 m0, s16, s8
	s_add_i32 s38, s24, 0x1a000
	v_lshl_add_u64 v[12:13], v[4:5], 0, s[0:1]
	s_mov_b64 s[0:1], 0x2a00
	global_load_lds_dwordx4 v[10:11], off
	s_mov_b32 m0, s25
	s_add_i32 s40, s24, 0x1c000
	v_lshl_add_u64 v[14:15], v[4:5], 0, s[0:1]
	s_mov_b64 s[0:1], 0x1200
	global_load_lds_dwordx4 v[12:13], off
	s_mov_b32 m0, s38
	v_and_b32_e32 v2, 48, v9
	s_add_i32 s41, s24, 0x1e000
	v_lshl_add_u64 v[16:17], v[4:5], 0, s[0:1]
	s_mov_b64 s[0:1], 0x2e00
	global_load_lds_dwordx4 v[14:15], off
	s_mov_b32 m0, s40
	global_load_dwordx4 v[0:3], v2, s[6:7]
	v_lshl_add_u64 v[4:5], v[4:5], 0, s[0:1]
	global_load_lds_dwordx4 v[16:17], off
	s_mov_b32 m0, s41
	v_lshlrev_b32_e32 v7, 4, v24
	global_load_lds_dwordx4 v[4:5], off
	v_readlane_b32 s1, v254, 37
	v_mov_b32_e32 v23, s14
	s_movk_i32 s0, 0x90
	v_add_u32_e32 v12, s1, v7
	v_readlane_b32 s1, v254, 38
	v_bfe_u32 v19, v9, 4, 2
	v_lshl_add_u32 v123, v18, 2, s14
	v_add_u32_e32 v13, s1, v7
	v_readlane_b32 s1, v254, 39
	s_lshl_b32 s17, s13, 8
	v_lshl_add_u32 v4, v18, 1, s14
	v_add_u32_e32 v14, s1, v7
	v_readlane_b32 s1, v254, 40
	v_mad_u32_u24 v126, v18, s0, v23
	v_mul_i32_i24_e32 v5, 0xffffff74, v18
	v_add_u32_e32 v15, s1, v7
	v_readlane_b32 s1, v254, 41
	v_cmp_gt_u32_e64 s[10:11], 16, v18
	v_and_b32_e32 v20, 15, v9
	v_add_u32_e32 v16, s1, v7
	v_readlane_b32 s1, v254, 42
	v_lshlrev_b32_e32 v21, 2, v19
	s_cmp_eq_u32 s13, 0
	v_add_u32_e32 v17, s1, v7
	v_readlane_b32 s1, v254, 43
	v_lshlrev_b32_e32 v127, 3, v19
	v_lshl_add_u32 v124, v20, 2, s14
	v_add_u32_e32 v18, s1, v7
	v_readlane_b32 s1, v254, 44
	s_cselect_b64 s[22:23], -1, 0
	s_cmp_eq_u32 s13, 1
	v_add_u32_e32 v19, s1, v7
	v_readlane_b32 s1, v254, 45
	v_or_b32_e32 v30, 2, v21
	v_add_u32_e32 v125, s17, v123
	v_add_u32_e32 v24, s1, v7
	v_readlane_b32 s1, v254, 46
	s_cselect_b64 s[6:7], -1, 0
	s_cmp_eq_u32 s13, 2
	v_or_b32_e32 v6, s46, v20
	v_add_u32_e32 v129, s17, v124
	v_add_u32_e32 v11, s16, v7
	v_add_u32_e32 v25, s1, v7
	v_readlane_b32 s1, v254, 47
	v_cmp_gt_u32_e64 s[16:17], v30, v20
	v_or_b32_e32 v30, 3, v21
	s_cselect_b64 s[8:9], -1, 0
	v_mad_u32_u24 v6, v6, s0, v23
	v_add_u32_e32 v26, s1, v7
	v_readlane_b32 s1, v254, 48
	v_cmp_gt_u32_e64 s[18:19], v30, v20
	v_mad_u32_u24 v23, v20, s0, v23
	v_bfe_u32 v30, v9, 3, 5
	s_add_i32 s0, s72, s33
	v_add_u32_e32 v27, s1, v7
	v_readlane_b32 s1, v254, 49
	s_mul_i32 s49, s20, 0xe00000
	v_mul_hi_u32_u24_e32 v31, 0x3800, v30
	v_mul_u32_u24_e32 v30, 0x3800, v30
	s_and_b32 s33, s0, 7
	v_and_b32_e32 v9, 7, v9
	v_add_u32_e32 v28, s1, v7
	v_readlane_b32 s1, v254, 50
	v_or_b32_e32 v30, s49, v30
	s_lshl_b32 s0, s33, 7
	v_lshlrev_b32_e32 v9, 4, v9
	v_add_u32_e32 v10, s12, v7
	v_add_u32_e32 v7, s1, v7
	s_mul_hi_i32 s48, s20, 0xe00000
	v_or3_b32 v92, v30, s0, v9
	s_lshl_b64 s[0:1], s[20:21], 22
	s_lshl_b32 s20, s33, 6
	s_or_b32 s20, s20, s46
	s_lshl_b32 s52, s13, 5
	v_add_u32_e32 v128, s14, v127
	s_mul_i32 s47, s13, 0x900
	v_cmp_gt_u32_e64 s[12:13], v21, v20
	v_cmp_lt_u32_e64 s[14:15], v21, v20
	v_or_b32_e32 v21, s20, v21
	v_lshlrev_b32_e32 v9, 11, v20
	v_lshlrev_b32_e32 v21, 1, v21
	v_mul_u32_u24_e32 v29, 0x90, v20
	v_or3_b32 v94, s0, v9, v21
	v_mul_hi_u32_u24_e32 v9, 0x1c00, v20
	v_mul_u32_u24_e32 v20, 0x1c00, v20
	s_waitcnt vmcnt(0)
	v_sub_f32_e32 v90, 1.0, v122
	v_or_b32_e32 v97, s48, v9
	v_or_b32_e32 v9, s49, v20
	v_mov_b32_e32 v98, 0
	v_mov_b32_e32 v91, v90
	v_or_b32_e32 v93, s48, v31
	v_mov_b32_e32 v95, s1
	v_or_b32_e32 v96, v9, v21
	s_mov_b32 s53, 32
	v_add_u32_e32 v130, v10, v22
	v_add_u32_e32 v131, v11, v22
	v_add_u32_e32 v132, v12, v22
	v_add_u32_e32 v133, v13, v22
	v_add_u32_e32 v134, v14, v22
	v_add_u32_e32 v135, v15, v22
	v_add_u32_e32 v136, v16, v22
	v_add_u32_e32 v137, v17, v22
	v_add_u32_e32 v138, v18, v22
	v_add_u32_e32 v139, v19, v22
	v_add_u32_e32 v140, v24, v22
	v_add_u32_e32 v141, v25, v22
	v_add_u32_e32 v142, v26, v22
	v_add_u32_e32 v143, v27, v22
	v_add_u32_e32 v144, v28, v22
	v_add_u32_e32 v145, v7, v22
	v_add_u32_e32 v146, s47, v4
	v_add_u32_e32 v147, v126, v5
	v_add_u32_e32 v148, v128, v29
	v_add_u32_e32 v149, v6, v127
	v_add_u32_e32 v150, v23, v127
	v_mov_b32_e32 v99, v98
	v_mov_b32_e32 v100, v98
	v_mov_b32_e32 v101, v98
	v_mov_b32_e32 v102, v98
	v_mov_b32_e32 v103, v98
	v_mov_b32_e32 v104, v98
	v_mov_b32_e32 v105, v98
	v_mov_b32_e32 v106, v98
	v_mov_b32_e32 v107, v98
	v_mov_b32_e32 v108, v98
	v_mov_b32_e32 v109, v98
	v_mov_b32_e32 v110, v98
	v_mov_b32_e32 v111, v98
	v_mov_b32_e32 v112, v98
	v_mov_b32_e32 v113, v98
	v_readfirstlane_b32 s0, v200
	s_nop 3
	s_lshr_b32 s0, s0, 8
	s_cmp_eq_u32 s0, 0
	s_cbranch_scc1 .LBB0_524
	s_barrier
	s_barrier
	s_branch .LBB0_524

; __global__ void __launch_bounds__(NTHR, 2) hymba_fwd(Args a) {
;     ...
;                 for (int u = blockIdx.x; u < 192; u += G) {
;     ...
;                     if (u < 64) ssd_unit(lds, P, u >> 1, u & 1);
;     ...
;                     if (u >= 64) hg_unit(lds, P, u - 64);
;     ...
;                     __syncthreads(); }
.Lhg_exit:
	v_readfirstlane_b32 s0, v200
	s_nop 3
	s_lshr_b32 s0, s0, 8
	s_cmp_eq_u32 s0, 0
	s_cbranch_scc0 .LBB0_495
	s_barrier
	s_barrier
	s_branch .LBB0_495
